# pre-pass units: separate LDS exchange buffers for the two unit kinds, one barrier per unit instead of two
# speedup vs baseline: 1.0058x; 1.0026x over previous
.Lpre_h_exch:
	v_mov_b32_e32 v32, v145
	v_mov_b32_e32 v33, v137
	ds_write_b64 v141, v[32:33]
	s_waitcnt lgkmcnt(0)
	s_barrier
	ds_read_b64 v[34:35], v140
	ds_read_b64 v[36:37], v140 offset:512
	ds_read_b64 v[38:39], v140 offset:1024
	ds_read_b64 v[40:41], v140 offset:1536
	s_waitcnt lgkmcnt(0)
	v_add_f32_e32 v42, v34, v36
	v_add_f32_e32 v43, v35, v37
	v_add_f32_e32 v42, v42, v38
	v_add_f32_e32 v43, v43, v39
	v_add_f32_e32 v42, v42, v40
	v_add_f32_e32 v43, v43, v41
	v_mov_b32_e32 v145, 0
	v_mov_b32_e32 v137, 0
	s_cmp_eq_u32 s17, 0
	s_cbranch_scc0 .Lpre_h_tpn
	s_mul_i32 s21, s19, 0xc00
	s_lshl_b32 s4, s18, 9
	s_add_u32 s21, s21, s4
	s_add_u32 s22, s21, 0x28d00000
	s_add_u32 s34, s94, s22
	s_addc_u32 s35, s95, 0
	v_mul_f32_e32 v44, s10, v42
	v_mul_f32_e32 v45, s10, v43
	v_exp_f32_e32 v44, v44
	v_exp_f32_e32 v45, v45
	s_nop 0
	global_store_dwordx2 v140, v[44:45], s[34:35]
	s_branch .Lpre_h_p2

.Lpre_g_exch:
	ds_write_b32 v144, v145 offset:6144
	s_waitcnt lgkmcnt(0)
	s_barrier
	ds_read_b32 v132, v142 offset:6144
	ds_read_b32 v133, v142 offset:6400
	ds_read_b32 v134, v142 offset:6656
	ds_read_b32 v135, v142 offset:6912
	s_waitcnt lgkmcnt(0)
	v_add_f32_e32 v136, v132, v133
	v_add_f32_e32 v136, v136, v134
	v_add_f32_e32 v136, v136, v135
	v_mov_b32_e32 v145, 0
	s_cmp_eq_u32 s17, 0
	s_cbranch_scc0 .Lpre_g_tpn
	s_mul_i32 s21, s19, 0xc00
	s_lshl_b32 s4, s18, 8
	s_add_u32 s21, s21, s4
	s_add_u32 s21, s21, 0x800
	s_add_u32 s22, s21, 0x28d00000
	s_add_u32 s36, s94, s22
	s_addc_u32 s37, s95, 0
	v_mul_f32_e32 v32, s10, v136
	v_exp_f32_e32 v32, v32
	s_nop 0
	global_store_dword v142, v32, s[36:37]
	s_branch .Lpre_g_p2
